# epilogue de-serialisation: ConvGLU per-column weights loaded once per tile half into spare quads, second half's loads/waits removed or issued ~2000 cycles early (on top of v40)
# speedup vs baseline: 1.0131x; 1.0027x over previous
; __device__ __forceinline__ unsigned pk2(float lo, float hi) { unsigned r; asm("v_cvt_pk_bf16_f32 %0, %1, %2" : "=v"(r) : "v"(lo), "v"(hi)); return r; }
;     __device__ bool next(int i, pg8::Unit& u) const { if (!base.next(i >> 1, u)) return false; u.seg = i & 1; return true; }
;     __device__ __forceinline__ void operator()(const f32x4 (&acc)[2][2][4][2], const pg8::Unit& u, int wr, int wc, int fr, int fq) const {
;     ...
;             for (int n = 0; n < 2; ++n) {
;                 const f32x4 w0 = *(const f32x4*)(cw + j0 + 4 * n), w1 = *(const f32x4*)(cw + DFF + j0 + 4 * n), w2 = *(const f32x4*)(cw + 2 * DFF + j0 + 4 * n), bs = *(const f32x4*)(cb + j0 + 4 * n);
;                 f32x4 o[4];
; #pragma unroll
;                 for (int e = 0; e < 4; ++e) {
;                     float t[4], sx[4];
; #pragma unroll
;                     for (int m = 0; m < 4; ++m) { const float gv = acc[ai][0][m][n][e]; t[m] = __shfl(gv, psrc); sx[m] = __shfl(gv, nsrc); }
; #pragma unroll
;                     for (int m = 0; m < 4; ++m) { const float gv = acc[ai][0][m][n][e];
;                         const float prev = (fr == 0) ? (m > 0 ? t[m > 0 ? m - 1 : 0] : 0.f) : t[m];
;                         const float next = (fr == 15) ? (m < 3 ? sx[m < 3 ? m + 1 : 3] : 0.f) : sx[m];
;                         const float y = w0[e] * prev + w1[e] * gv + w2[e] * next + bs[e];
;                         o[m][e] = gelu_f(y) * acc[ai][1][m][n][e]; } }
; #pragma unroll
;                 for (int m = 0; m < 4; ++m) { const int rho = 16 * m + fr;
;                     if (rho != 0 && rho != 63) { u32x2 wv; wv.x = pk2(o[m][0], o[m][1]); wv.y = pk2(o[m][2], o[m][3]);
;                         *(u32x2*)(act + (size_t)(kb * 64 + rho) * DFF + j0 + 4 * n) = wv; } }
.LBB0_891:
	s_or_b64 exec, exec, s[14:15]
	v_readlane_b32 s76, v246, 25
	v_readlane_b32 s88, v246, 37
	v_readlane_b32 s89, v246, 38
	v_readlane_b32 s90, v246, 39
	v_readlane_b32 s91, v246, 40
	s_mov_b64 s[16:17], s[88:89]
	v_lshlrev_b64 v[128:129], 2, v[168:169]
	s_mov_b64 s[18:19], s[90:91]
	v_lshl_add_u64 v[170:171], s[16:17], 0, v[128:129]
	v_lshl_add_u64 v[176:177], s[40:41], 0, v[128:129]
	v_lshl_add_u64 v[172:173], s[18:19], 0, v[128:129]
	v_lshl_add_u64 v[174:175], s[38:39], 0, v[128:129]
	global_load_dwordx4 v[140:143], v[170:171], off
	global_load_dwordx4 v[132:135], v[174:175], off
	global_load_dwordx4 v[136:139], v[176:177], off
	global_load_dwordx4 v[128:131], v[172:173], off
	global_load_dwordx4 v[226:229], v[170:171], off
	global_load_dwordx4 v[230:233], v[174:175], off
	global_load_dwordx4 v[234:237], v[176:177], off
	global_load_dwordx4 v[238:241], v[172:173], off
	ds_bpermute_b32 v180, v190, v120
	ds_bpermute_b32 v218, v191, v120
	ds_bpermute_b32 v211, v190, v116
	ds_bpermute_b32 v212, v191, v116
	ds_bpermute_b32 v215, v190, v112
	ds_bpermute_b32 v213, v191, v112
	ds_bpermute_b32 v217, v190, v100
	ds_bpermute_b32 v216, v191, v100
	ds_bpermute_b32 v181, v190, v121
	ds_bpermute_b32 v219, v191, v121
	ds_bpermute_b32 v209, v190, v117
	ds_bpermute_b32 v214, v191, v117
	ds_bpermute_b32 v206, v190, v113
	ds_bpermute_b32 v210, v191, v113
	ds_bpermute_b32 v207, v190, v101
	ds_bpermute_b32 v208, v191, v101
	ds_bpermute_b32 v178, v190, v122
	ds_bpermute_b32 v220, v191, v122
	ds_bpermute_b32 v199, v190, v118
	ds_bpermute_b32 v200, v191, v118
	ds_bpermute_b32 v203, v190, v114
	ds_bpermute_b32 v201, v191, v114
	ds_bpermute_b32 v205, v190, v102
	ds_bpermute_b32 v204, v191, v102
	ds_bpermute_b32 v179, v190, v123
	ds_bpermute_b32 v221, v191, v123
	ds_bpermute_b32 v197, v190, v119
	ds_bpermute_b32 v202, v191, v119
	ds_bpermute_b32 v194, v190, v115
	ds_bpermute_b32 v198, v191, v115
	ds_bpermute_b32 v195, v190, v103
	ds_bpermute_b32 v196, v191, v103
	s_lshl_b32 s49, s47, 6
	v_or_b32_e32 v193, s49, v145
	v_readlane_b32 s77, v246, 26
	v_readlane_b32 s78, v246, 27
	v_readlane_b32 s79, v246, 28
	v_readlane_b32 s80, v246, 29
	v_readlane_b32 s81, v246, 30
	v_readlane_b32 s82, v246, 31
	v_readlane_b32 s83, v246, 32
	v_readlane_b32 s84, v246, 33
	v_readlane_b32 s85, v246, 34
	v_readlane_b32 s86, v246, 35
	v_readlane_b32 s87, v246, 36
	s_and_saveexec_b64 s[14:15], s[8:9]
	s_cbranch_execz .LBB0_893
	s_waitcnt lgkmcnt(0)
	v_cndmask_b32_e64 v223, v221, v202, s[4:5]
	v_mov_b32_e32 v224, v123
	s_waitcnt vmcnt(0)
	v_mov_b32_e32 v225, v139
	v_mov_b32_e32 v222, v135
	v_cndmask_b32_e64 v221, v220, v200, s[4:5]
	v_mov_b32_e32 v123, v138
	v_mov_b32_e32 v220, v134
	v_pk_mul_f32 v[222:223], v[224:225], v[222:223]
	v_pk_mul_f32 v[122:123], v[122:123], v[220:221]
	v_mov_b32_e32 v221, v222
	v_mov_b32_e32 v220, v122
	v_pk_fma_f32 v[220:221], v[142:143], v[178:179], v[220:221]
	v_mov_b32_e32 v222, v123
	v_pk_add_f32 v[122:123], v[220:221], v[222:223]
	s_nop 0
	v_pk_add_f32 v[122:123], v[130:131], v[122:123]
	s_nop 0
	v_fma_f32 v220, |v123|, s74, 1.0
	v_rcp_f32_e32 v222, v220
	v_pk_mul_f32 v[220:221], v[122:123], v[122:123]
	v_cmp_gt_f32_e32 vcc, 0, v123
	v_mul_f32_e32 v221, 0xbf38aa3b, v221
	v_fmamk_f32 v223, v222, 0x3f07dc22, v192
	v_exp_f32_e32 v221, v221
	v_fmaak_f32 v223, v222, v223, 0x3f35f0e3
	v_fmaak_f32 v223, v222, v223, 0xbe11a98e
	v_fmaak_f32 v223, v222, v223, 0x3e027906
	v_mul_f32_e32 v222, v222, v223
	v_mul_f32_e32 v221, v221, v222
	v_mul_f32_e32 v222, v123, v221
	v_fma_f32 v221, -v123, v221, v123
	v_cndmask_b32_e32 v123, v221, v222, vcc
	v_fma_f32 v221, |v122|, s74, 1.0
	v_rcp_f32_e32 v221, v221
	v_mul_f32_e32 v222, v127, v123
	v_mul_f32_e32 v123, 0xbf38aa3b, v220
	v_exp_f32_e32 v123, v123
	v_fmamk_f32 v127, v221, 0x3f07dc22, v192
	v_fmaak_f32 v127, v221, v127, 0x3f35f0e3
	v_fmaak_f32 v127, v221, v127, 0xbe11a98e
	v_fmaak_f32 v127, v221, v127, 0x3e027906
	v_mul_f32_e32 v127, v221, v127
	v_mul_f32_e32 v123, v123, v127
	v_mul_f32_e32 v127, v122, v123
	v_fma_f32 v123, -v122, v123, v122
	v_cmp_gt_f32_e32 vcc, 0, v122
	s_nop 1
	v_cndmask_b32_e32 v122, v123, v127, vcc
	v_mul_f32_e32 v220, v126, v122
	v_cndmask_b32_e64 v123, v219, v214, s[4:5]
	v_mov_b32_e32 v126, v121
	v_mov_b32_e32 v127, v137
	v_mov_b32_e32 v122, v133
	v_pk_mul_f32 v[122:123], v[126:127], v[122:123]
	v_cndmask_b32_e64 v127, v218, v212, s[4:5]
	v_mov_b32_e32 v121, v136
	v_mov_b32_e32 v126, v132
	v_pk_mul_f32 v[120:121], v[120:121], v[126:127]
	v_mov_b32_e32 v127, v122
	v_mov_b32_e32 v126, v120
	v_pk_fma_f32 v[126:127], v[140:141], v[180:181], v[126:127]
	v_mov_b32_e32 v122, v121
	v_pk_add_f32 v[120:121], v[126:127], v[122:123]
	s_nop 0
	v_pk_add_f32 v[120:121], v[128:129], v[120:121]
	s_nop 0
	v_fma_f32 v122, |v121|, s74, 1.0
	v_rcp_f32_e32 v126, v122
	v_pk_mul_f32 v[122:123], v[120:121], v[120:121]
	v_cmp_gt_f32_e32 vcc, 0, v121
	v_mul_f32_e32 v123, 0xbf38aa3b, v123
	v_fmamk_f32 v127, v126, 0x3f07dc22, v192
	v_exp_f32_e32 v123, v123
	v_fmaak_f32 v127, v126, v127, 0x3f35f0e3
	v_fmaak_f32 v127, v126, v127, 0xbe11a98e
	v_fmaak_f32 v127, v126, v127, 0x3e027906
	v_mul_f32_e32 v126, v126, v127
	v_mul_f32_e32 v123, v123, v126
	v_mul_f32_e32 v126, v121, v123
	v_fma_f32 v123, -v121, v123, v121
	v_cndmask_b32_e32 v121, v123, v126, vcc
	v_fma_f32 v123, |v120|, s74, 1.0
	v_rcp_f32_e32 v123, v123
	v_mul_f32_e32 v121, v125, v121
	v_mul_f32_e32 v122, 0xbf38aa3b, v122
	v_exp_f32_e32 v122, v122
	v_fmamk_f32 v125, v123, 0x3f07dc22, v192
	v_fmaak_f32 v125, v123, v125, 0x3f35f0e3
	v_fmaak_f32 v125, v123, v125, 0xbe11a98e
	v_fmaak_f32 v125, v123, v125, 0x3e027906
	v_mul_f32_e32 v123, v123, v125
	v_mul_f32_e32 v122, v122, v123
	v_mul_f32_e32 v123, v120, v122
	v_fma_f32 v122, -v120, v122, v120
	v_cmp_gt_f32_e32 vcc, 0, v120
	s_nop 1
	v_cndmask_b32_e32 v120, v122, v123, vcc
	v_mov_b64_e32 v[122:123], s[26:27]
	v_mad_i64_i32 v[122:123], s[16:17], v193, s75, v[122:123]
	v_mul_f32_e32 v120, v124, v120
	v_lshl_add_u64 v[122:123], v[168:169], 1, v[122:123]
	v_cvt_pk_bf16_f32 v120, v120, v121
	v_cvt_pk_bf16_f32 v121, v220, v222
	global_store_dwordx2 v[122:123], v[120:121], off

; __device__ __forceinline__ unsigned pk2(float lo, float hi) { unsigned r; asm("v_cvt_pk_bf16_f32 %0, %1, %2" : "=v"(r) : "v"(lo), "v"(hi)); return r; }
;     __device__ bool next(int i, pg8::Unit& u) const { if (!base.next(i >> 1, u)) return false; u.seg = i & 1; return true; }
;     __device__ __forceinline__ void operator()(const f32x4 (&acc)[2][2][4][2], const pg8::Unit& u, int wr, int wc, int fr, int fq) const {
;     ...
;             for (int n = 0; n < 2; ++n) {
;                 const f32x4 w0 = *(const f32x4*)(cw + j0 + 4 * n), w1 = *(const f32x4*)(cw + DFF + j0 + 4 * n), w2 = *(const f32x4*)(cw + 2 * DFF + j0 + 4 * n), bs = *(const f32x4*)(cb + j0 + 4 * n);
;                 f32x4 o[4];
; #pragma unroll
;                 for (int e = 0; e < 4; ++e) {
;                     float t[4], sx[4];
; #pragma unroll
;                     for (int m = 0; m < 4; ++m) { const float gv = acc[ai][0][m][n][e]; t[m] = __shfl(gv, psrc); sx[m] = __shfl(gv, nsrc); }
; #pragma unroll
;                     for (int m = 0; m < 4; ++m) { const float gv = acc[ai][0][m][n][e];
;                         const float prev = (fr == 0) ? (m > 0 ? t[m > 0 ? m - 1 : 0] : 0.f) : t[m];
;                         const float next = (fr == 15) ? (m < 3 ? sx[m < 3 ? m + 1 : 3] : 0.f) : sx[m];
;                         const float y = w0[e] * prev + w1[e] * gv + w2[e] * next + bs[e];
;                         o[m][e] = gelu_f(y) * acc[ai][1][m][n][e]; } }
; #pragma unroll
;                 for (int m = 0; m < 4; ++m) { const int rho = 16 * m + fr;
;                     if (rho != 0 && rho != 63) { u32x2 wv; wv.x = pk2(o[m][0], o[m][1]); wv.y = pk2(o[m][2], o[m][3]);
;                         *(u32x2*)(act + (size_t)(kb * 64 + rho) * DFF + j0 + 4 * n) = wv; } }
.LBB0_905:
	s_or_b64 exec, exec, s[14:15]
	v_mov_b32_e32 v76, v226
	v_mov_b32_e32 v77, v227
	v_mov_b32_e32 v78, v228
	v_mov_b32_e32 v79, v229
	v_mov_b32_e32 v68, v230
	v_mov_b32_e32 v69, v231
	v_mov_b32_e32 v70, v232
	v_mov_b32_e32 v71, v233
	v_mov_b32_e32 v72, v234
	v_mov_b32_e32 v73, v235
	v_mov_b32_e32 v74, v236
	v_mov_b32_e32 v75, v237
	v_mov_b32_e32 v64, v238
	v_mov_b32_e32 v65, v239
	v_mov_b32_e32 v66, v240
	v_mov_b32_e32 v67, v241
	global_load_dwordx4 v[226:229], v[170:171], off offset:16
	global_load_dwordx4 v[230:233], v[80:81], off
	global_load_dwordx4 v[234:237], v[82:83], off
	global_load_dwordx4 v[238:241], v[172:173], off offset:16
	ds_bpermute_b32 v86, v190, v60
	ds_bpermute_b32 v115, v191, v60
	ds_bpermute_b32 v106, v190, v52
	ds_bpermute_b32 v107, v191, v52
	ds_bpermute_b32 v110, v190, v48
	ds_bpermute_b32 v108, v191, v48
	ds_bpermute_b32 v114, v190, v44
	ds_bpermute_b32 v111, v191, v44
	ds_bpermute_b32 v87, v190, v61
	ds_bpermute_b32 v116, v191, v61
	ds_bpermute_b32 v104, v190, v53
	ds_bpermute_b32 v109, v191, v53
	ds_bpermute_b32 v101, v190, v49
	ds_bpermute_b32 v105, v191, v49
	ds_bpermute_b32 v102, v190, v45
	ds_bpermute_b32 v103, v191, v45
	ds_bpermute_b32 v84, v190, v62
	ds_bpermute_b32 v117, v191, v62
	ds_bpermute_b32 v94, v190, v54
	ds_bpermute_b32 v95, v191, v54
	ds_bpermute_b32 v98, v190, v50
	ds_bpermute_b32 v96, v191, v50
	ds_bpermute_b32 v100, v190, v46
	ds_bpermute_b32 v99, v191, v46
	ds_bpermute_b32 v85, v190, v63
	ds_bpermute_b32 v118, v191, v63
	ds_bpermute_b32 v92, v190, v55
	ds_bpermute_b32 v97, v191, v55
	ds_bpermute_b32 v89, v190, v51
	ds_bpermute_b32 v93, v191, v51
	ds_bpermute_b32 v90, v190, v47
	ds_bpermute_b32 v91, v191, v47
	s_lshl_b32 s47, s18, 6
	v_or_b32_e32 v88, s47, v145
	s_and_saveexec_b64 s[14:15], s[8:9]
	s_cbranch_execz .LBB0_907
	s_waitcnt lgkmcnt(4)
	v_cndmask_b32_e64 v119, v118, v97, s[4:5]
	v_mov_b32_e32 v120, v63
	v_mov_b32_e32 v121, v75
	v_mov_b32_e32 v118, v71
	v_pk_mul_f32 v[118:119], v[120:121], v[118:119]
	v_cndmask_b32_e64 v121, v117, v95, s[4:5]
	v_mov_b32_e32 v63, v74
	v_mov_b32_e32 v120, v70
	v_pk_mul_f32 v[62:63], v[62:63], v[120:121]
	v_mov_b32_e32 v121, v118
	v_mov_b32_e32 v120, v62
	v_pk_fma_f32 v[120:121], v[78:79], v[84:85], v[120:121]
	v_mov_b32_e32 v118, v63
	v_pk_add_f32 v[62:63], v[120:121], v[118:119]
	v_pk_add_f32 v[62:63], v[66:67], v[62:63]
	s_nop 0
	v_fma_f32 v117, |v63|, s74, 1.0
	v_rcp_f32_e32 v117, v117
	v_pk_mul_f32 v[118:119], v[62:63], v[62:63]
	v_cmp_gt_f32_e32 vcc, 0, v63
	v_mul_f32_e32 v119, 0xbf38aa3b, v119
	v_fmamk_f32 v120, v117, 0x3f07dc22, v192
	v_exp_f32_e32 v119, v119
	v_fmaak_f32 v120, v117, v120, 0x3f35f0e3
	v_fmaak_f32 v120, v117, v120, 0xbe11a98e
	v_fmaak_f32 v120, v117, v120, 0x3e027906
	v_mul_f32_e32 v117, v117, v120
	v_mul_f32_e32 v117, v119, v117
	v_mul_f32_e32 v119, v63, v117
	v_fma_f32 v117, -v63, v117, v63
	v_cndmask_b32_e32 v63, v117, v119, vcc
	v_fma_f32 v117, |v62|, s74, 1.0
	v_rcp_f32_e32 v117, v117
	v_mul_f32_e32 v119, v59, v63
	v_mul_f32_e32 v59, 0xbf38aa3b, v118
	v_exp_f32_e32 v59, v59
	v_fmamk_f32 v63, v117, 0x3f07dc22, v192
	v_fmaak_f32 v63, v117, v63, 0x3f35f0e3
	v_fmaak_f32 v63, v117, v63, 0xbe11a98e
	v_fmaak_f32 v63, v117, v63, 0x3e027906
	v_mul_f32_e32 v63, v117, v63
	v_mul_f32_e32 v59, v59, v63
	v_mul_f32_e32 v63, v62, v59
	v_fma_f32 v59, -v62, v59, v62
	v_cmp_gt_f32_e32 vcc, 0, v62
	v_mov_b32_e32 v62, v61
	v_mov_b32_e32 v61, v72
	v_cndmask_b32_e32 v59, v59, v63, vcc
	v_mul_f32_e32 v117, v58, v59
	v_cndmask_b32_e64 v59, v116, v109, s[4:5]
	v_mov_b32_e32 v63, v73
	v_mov_b32_e32 v58, v69
	v_pk_mul_f32 v[58:59], v[62:63], v[58:59]
	v_cndmask_b32_e64 v63, v115, v107, s[4:5]
	v_mov_b32_e32 v62, v68
	v_pk_mul_f32 v[60:61], v[60:61], v[62:63]
	v_mov_b32_e32 v63, v58
	v_mov_b32_e32 v62, v60
	v_pk_fma_f32 v[62:63], v[76:77], v[86:87], v[62:63]
	v_mov_b32_e32 v58, v61
	v_pk_add_f32 v[58:59], v[62:63], v[58:59]
	s_nop 0
	v_pk_add_f32 v[58:59], v[64:65], v[58:59]
	s_nop 0
	v_fma_f32 v60, |v59|, s74, 1.0
	v_rcp_f32_e32 v62, v60
	v_pk_mul_f32 v[60:61], v[58:59], v[58:59]
	v_cmp_gt_f32_e32 vcc, 0, v59
	v_mul_f32_e32 v61, 0xbf38aa3b, v61
	v_fmamk_f32 v63, v62, 0x3f07dc22, v192
	v_exp_f32_e32 v61, v61
	v_fmaak_f32 v63, v62, v63, 0x3f35f0e3
	v_fmaak_f32 v63, v62, v63, 0xbe11a98e
	v_fmaak_f32 v63, v62, v63, 0x3e027906
	v_mul_f32_e32 v62, v62, v63
	v_mul_f32_e32 v61, v61, v62
	v_mul_f32_e32 v62, v59, v61
	v_fma_f32 v61, -v59, v61, v59
	v_cndmask_b32_e32 v59, v61, v62, vcc
	v_fma_f32 v61, |v58|, s74, 1.0
	v_rcp_f32_e32 v61, v61
	v_mul_f32_e32 v57, v57, v59
	v_mul_f32_e32 v59, 0xbf38aa3b, v60
	v_exp_f32_e32 v59, v59
	v_fmamk_f32 v60, v61, 0x3f07dc22, v192
	v_fmaak_f32 v60, v61, v60, 0x3f35f0e3
	v_fmaak_f32 v60, v61, v60, 0xbe11a98e
	v_fmaak_f32 v60, v61, v60, 0x3e027906
	v_mul_f32_e32 v60, v61, v60
	v_mul_f32_e32 v59, v59, v60
	v_mul_f32_e32 v60, v58, v59
	v_fma_f32 v59, -v58, v59, v58
	v_cmp_gt_f32_e32 vcc, 0, v58
	s_nop 1
	v_cndmask_b32_e32 v58, v59, v60, vcc
	v_mul_f32_e32 v56, v56, v58
	v_mov_b64_e32 v[58:59], s[26:27]
	v_mad_i64_i32 v[58:59], s[16:17], v88, s75, v[58:59]
	v_lshl_add_u64 v[58:59], v[168:169], 1, v[58:59]
	v_cvt_pk_bf16_f32 v56, v56, v57
	v_cvt_pk_bf16_f32 v57, v117, v119
	global_store_dwordx2 v[58:59], v[56:57], off
; __device__ __forceinline__ unsigned pk2(float lo, float hi) { unsigned r; asm("v_cvt_pk_bf16_f32 %0, %1, %2" : "=v"(r) : "v"(lo), "v"(hi)); return r; }
;     __device__ bool next(int i, pg8::Unit& u) const { if (!base.next(i >> 1, u)) return false; u.seg = i & 1; return true; }
;     __device__ __forceinline__ void operator()(const f32x4 (&acc)[2][2][4][2], const pg8::Unit& u, int wr, int wc, int fr, int fq) const {
;     ...
;             for (int n = 0; n < 2; ++n) {
;                 const f32x4 w0 = *(const f32x4*)(cw + j0 + 4 * n), w1 = *(const f32x4*)(cw + DFF + j0 + 4 * n), w2 = *(const f32x4*)(cw + 2 * DFF + j0 + 4 * n), bs = *(const f32x4*)(cb + j0 + 4 * n);
;                 f32x4 o[4];
; #pragma unroll
;                 for (int e = 0; e < 4; ++e) {
;                     float t[4], sx[4];
; #pragma unroll
;                     for (int m = 0; m < 4; ++m) { const float gv = acc[ai][0][m][n][e]; t[m] = __shfl(gv, psrc); sx[m] = __shfl(gv, nsrc); }
; #pragma unroll
;                     for (int m = 0; m < 4; ++m) { const float gv = acc[ai][0][m][n][e];
;                         const float prev = (fr == 0) ? (m > 0 ? t[m > 0 ? m - 1 : 0] : 0.f) : t[m];
;                         const float next = (fr == 15) ? (m < 3 ? sx[m < 3 ? m + 1 : 3] : 0.f) : sx[m];
;                         const float y = w0[e] * prev + w1[e] * gv + w2[e] * next + bs[e];
;                         o[m][e] = gelu_f(y) * acc[ai][1][m][n][e]; } }
; #pragma unroll
;                 for (int m = 0; m < 4; ++m) { const int rho = 16 * m + fr;
;                     if (rho != 0 && rho != 63) { u32x2 wv; wv.x = pk2(o[m][0], o[m][1]); wv.y = pk2(o[m][2], o[m][3]);
;                         *(u32x2*)(act + (size_t)(kb * 64 + rho) * DFF + j0 + 4 * n) = wv; } }
.LBB0_907:
	s_or_b64 exec, exec, s[14:15]
	v_mov_b32_e32 v60, v76
	v_mov_b32_e32 v61, v72
	s_waitcnt lgkmcnt(14)
	v_cndmask_b32_e64 v56, v114, v110, s[10:11]
	v_cndmask_b32_e64 v57, v111, 0, s[4:5]
	v_cndmask_b32_e64 v58, v110, v106, s[10:11]
	v_cndmask_b32_e64 v59, v108, v111, s[4:5]
	v_pk_mul_f32 v[56:57], v[60:61], v[56:57]
	v_pk_mul_f32 v[58:59], v[60:61], v[58:59]
	v_mov_b32_e32 v62, v44
	v_mov_b32_e32 v63, v48
	v_mov_b32_e32 v110, v56
	v_mov_b32_e32 v111, v58
	v_pk_fma_f32 v[62:63], v[62:63], v[68:69], v[110:111] op_sel_hi:[1,0,1]
	v_mov_b32_e32 v58, v57
	v_pk_add_f32 v[56:57], v[62:63], v[58:59]
	v_cndmask_b32_e64 v62, v106, v86, s[10:11]
	v_pk_add_f32 v[56:57], v[64:65], v[56:57] op_sel_hi:[0,1]
	v_fma_f32 v44, |v57|, s74, 1.0
	v_rcp_f32_e32 v44, v44
	v_cndmask_b32_e64 v63, v107, v108, s[4:5]
	v_pk_mul_f32 v[58:59], v[56:57], v[56:57]
	v_pk_mul_f32 v[60:61], v[60:61], v[62:63]
	v_cndmask_b32_e64 v62, v104, v87, s[10:11]
	v_cndmask_b32_e64 v63, v109, v105, s[4:5]
	v_mov_b32_e32 v72, v77
	v_fmamk_f32 v48, v44, 0x3f07dc22, v192
	v_mul_f32_e32 v59, 0xbf38aa3b, v59
	v_pk_mul_f32 v[62:63], v[72:73], v[62:63]
	v_fmaak_f32 v48, v44, v48, 0x3f35f0e3
	v_exp_f32_e32 v59, v59
	v_mov_b32_e32 v76, v60
	v_mov_b32_e32 v77, v62
	v_fmaak_f32 v48, v44, v48, 0xbe11a98e
	v_pk_fma_f32 v[52:53], v[52:53], v[68:69], v[76:77]
	v_mov_b32_e32 v62, v61
	v_fmaak_f32 v48, v44, v48, 0x3e027906
	v_pk_add_f32 v[52:53], v[52:53], v[62:63]
	v_mul_f32_e32 v44, v44, v48
	v_pk_add_f32 v[52:53], v[64:65], v[52:53]
	v_mul_f32_e32 v44, v59, v44
	v_fma_f32 v59, |v52|, s74, 1.0
	v_rcp_f32_e32 v59, v59
	v_mul_f32_e32 v48, v57, v44
	v_fma_f32 v44, -v57, v44, v57
	v_cmp_gt_f32_e64 s[14:15], 0, v57
	v_pk_mul_f32 v[60:61], v[52:53], v[52:53]
	v_cndmask_b32_e64 v62, v102, v101, s[10:11]
	v_cndmask_b32_e64 v44, v44, v48, s[14:15]
	v_mul_f32_e32 v57, v36, v44
	v_fmamk_f32 v36, v59, 0x3f07dc22, v192
	v_mul_f32_e32 v44, 0xbf38aa3b, v60
	v_fmaak_f32 v36, v59, v36, 0x3f35f0e3
	v_exp_f32_e32 v44, v44
	v_fmaak_f32 v36, v59, v36, 0xbe11a98e
	v_fmaak_f32 v36, v59, v36, 0x3e027906
	v_fma_f32 v48, |v53|, s74, 1.0
	v_mul_f32_e32 v36, v59, v36
	v_rcp_f32_e32 v48, v48
	v_mul_f32_e32 v36, v44, v36
	v_mul_f32_e32 v44, v52, v36
	v_fma_f32 v36, -v52, v36, v52
	v_cmp_gt_f32_e64 s[14:15], 0, v52
	v_cndmask_b32_e64 v60, v101, v104, s[10:11]
	v_cndmask_b32_e64 v63, v103, 0, s[4:5]
	v_cndmask_b32_e64 v36, v36, v44, s[14:15]
	v_mul_f32_e32 v59, v40, v36
	v_fmamk_f32 v36, v48, 0x3f07dc22, v192
	v_fmaak_f32 v36, v48, v36, 0x3f35f0e3
	v_mul_f32_e32 v40, 0xbf38aa3b, v61
	v_fmaak_f32 v36, v48, v36, 0xbe11a98e
	v_cndmask_b32_e64 v61, v105, v103, s[4:5]
	v_fmaak_f32 v36, v48, v36, 0x3e027906
	v_pk_mul_f32 v[60:61], v[72:73], v[60:61]
	v_pk_mul_f32 v[62:63], v[72:73], v[62:63]
	v_mul_f32_e32 v36, v48, v36
	v_mov_b32_e32 v48, v45
	v_mov_b32_e32 v44, v62
	v_mov_b32_e32 v45, v60
	v_pk_fma_f32 v[44:45], v[48:49], v[68:69], v[44:45] op_sel:[0,1,0]
	v_mov_b32_e32 v60, v63
	v_exp_f32_e32 v40, v40
	v_pk_add_f32 v[44:45], v[44:45], v[60:61]
	v_cmp_gt_f32_e64 s[14:15], 0, v53
	v_pk_add_f32 v[44:45], v[64:65], v[44:45] op_sel:[1,0]
	v_mul_f32_e32 v36, v40, v36
	v_fma_f32 v48, |v45|, s74, 1.0
	v_rcp_f32_e32 v48, v48
	v_mul_f32_e32 v40, v53, v36
	v_fma_f32 v36, -v53, v36, v53
	v_cndmask_b32_e64 v36, v36, v40, s[14:15]
	v_mul_f32_e32 v68, v41, v36
	v_fmamk_f32 v36, v48, 0x3f07dc22, v192
	v_fmaak_f32 v36, v48, v36, 0x3f35f0e3
	v_pk_mul_f32 v[40:41], v[44:45], v[44:45]
	v_fmaak_f32 v36, v48, v36, 0xbe11a98e
	v_mul_f32_e32 v41, 0xbf38aa3b, v41
	v_fmaak_f32 v36, v48, v36, 0x3e027906
	v_exp_f32_e32 v41, v41
	v_mul_f32_e32 v36, v48, v36
	v_mov_b32_e32 v48, v78
	v_mov_b32_e32 v49, v74
	s_waitcnt lgkmcnt(9)
	v_cndmask_b32_e64 v52, v100, v98, s[10:11]
	s_waitcnt lgkmcnt(8)
	v_cndmask_b32_e64 v53, v99, 0, s[4:5]
	v_cndmask_b32_e64 v60, v98, v94, s[10:11]
	v_cndmask_b32_e64 v61, v96, v99, s[4:5]
	v_pk_mul_f32 v[52:53], v[48:49], v[52:53]
	v_pk_mul_f32 v[60:61], v[48:49], v[60:61]
	v_mov_b32_e32 v62, v46
	v_mov_b32_e32 v63, v50
	v_mov_b32_e32 v64, v52
	v_mov_b32_e32 v65, v60
	v_pk_fma_f32 v[62:63], v[62:63], v[70:71], v[64:65] op_sel_hi:[1,0,1]
	v_mov_b32_e32 v60, v53
	v_mul_f32_e32 v36, v41, v36
	v_pk_add_f32 v[52:53], v[62:63], v[60:61]
	v_mul_f32_e32 v41, v45, v36
	v_fma_f32 v36, -v45, v36, v45
	v_cmp_gt_f32_e64 s[16:17], 0, v45
	v_pk_add_f32 v[52:53], v[66:67], v[52:53] op_sel_hi:[0,1]
	v_cndmask_b32_e64 v60, v94, v84, s[10:11]
	v_cndmask_b32_e64 v36, v36, v41, s[16:17]
	v_fma_f32 v41, |v53|, s74, 1.0
	v_rcp_f32_e32 v41, v41
	v_cndmask_b32_e64 v61, v95, v96, s[4:5]
	v_pk_mul_f32 v[48:49], v[48:49], v[60:61]
	s_waitcnt lgkmcnt(5)
	v_cndmask_b32_e64 v60, v92, v85, s[10:11]
	s_waitcnt lgkmcnt(2)
	v_cndmask_b32_e64 v61, v97, v93, s[4:5]
	v_mov_b32_e32 v74, v79
	v_pk_mul_f32 v[60:61], v[74:75], v[60:61]
	v_mul_f32_e32 v45, v37, v36
	v_pk_mul_f32 v[36:37], v[52:53], v[52:53]
	v_fmamk_f32 v46, v41, 0x3f07dc22, v192
	v_mov_b32_e32 v62, v48
	v_mov_b32_e32 v63, v60
	v_fmaak_f32 v46, v41, v46, 0x3f35f0e3
	v_mul_f32_e32 v37, 0xbf38aa3b, v37
	v_pk_fma_f32 v[54:55], v[54:55], v[70:71], v[62:63]
	v_mov_b32_e32 v60, v49
	v_exp_f32_e32 v37, v37
	v_fmaak_f32 v46, v41, v46, 0xbe11a98e
	v_pk_add_f32 v[48:49], v[54:55], v[60:61]
	v_fmaak_f32 v46, v41, v46, 0x3e027906
	v_pk_add_f32 v[48:49], v[66:67], v[48:49]
	v_mul_f32_e32 v41, v41, v46
	v_fma_f32 v46, |v48|, s74, 1.0
	v_rcp_f32_e32 v46, v46
	v_mul_f32_e32 v37, v37, v41
	v_mul_f32_e32 v41, v53, v37
	v_fma_f32 v37, -v53, v37, v53
	v_cmp_gt_f32_e64 s[18:19], 0, v53
	v_pk_mul_f32 v[54:55], v[48:49], v[48:49]
	s_waitcnt lgkmcnt(1)
; __device__ __forceinline__ unsigned pk2(float lo, float hi) { unsigned r; asm("v_cvt_pk_bf16_f32 %0, %1, %2" : "=v"(r) : "v"(lo), "v"(hi)); return r; }
;     __device__ bool next(int i, pg8::Unit& u) const { if (!base.next(i >> 1, u)) return false; u.seg = i & 1; return true; }
;     __device__ __forceinline__ void operator()(const f32x4 (&acc)[2][2][4][2], const pg8::Unit& u, int wr, int wc, int fr, int fq) const {
;     ...
;                     for (int m = 0; m < 4; ++m) { const float gv = acc[ai][0][m][n][e];
;                         const float prev = (fr == 0) ? (m > 0 ? t[m > 0 ? m - 1 : 0] : 0.f) : t[m];
;                         const float next = (fr == 15) ? (m < 3 ? sx[m < 3 ? m + 1 : 3] : 0.f) : sx[m];
;                         const float y = w0[e] * prev + w1[e] * gv + w2[e] * next + bs[e];
;                         o[m][e] = gelu_f(y) * acc[ai][1][m][n][e]; } }
; #pragma unroll
;                 for (int m = 0; m < 4; ++m) { const int rho = 16 * m + fr;
;                     if (rho != 0 && rho != 63) { u32x2 wv; wv.x = pk2(o[m][0], o[m][1]); wv.y = pk2(o[m][2], o[m][3]);
;                         *(u32x2*)(act + (size_t)(kb * 64 + rho) * DFF + j0 + 4 * n) = wv; } }
	v_cndmask_b32_e64 v60, v90, v89, s[10:11]
	v_cndmask_b32_e64 v37, v37, v41, s[18:19]
	v_mul_f32_e32 v37, v38, v37
	v_fmamk_f32 v38, v46, 0x3f07dc22, v192
	v_fmaak_f32 v38, v46, v38, 0x3f35f0e3
	v_mul_f32_e32 v41, 0xbf38aa3b, v54
	v_exp_f32_e32 v41, v41
	v_fmaak_f32 v38, v46, v38, 0xbe11a98e
	v_fmaak_f32 v38, v46, v38, 0x3e027906
	v_mul_f32_e32 v38, v46, v38
	v_fma_f32 v46, |v49|, s74, 1.0
	v_rcp_f32_e32 v46, v46
	v_mul_f32_e32 v38, v41, v38
	v_mul_f32_e32 v41, v48, v38
	v_fma_f32 v38, -v48, v38, v48
	v_cmp_gt_f32_e64 s[18:19], 0, v48
	v_cndmask_b32_e64 v54, v89, v92, s[10:11]
	s_waitcnt lgkmcnt(0)
	v_cndmask_b32_e64 v61, v91, 0, s[4:5]
	v_cndmask_b32_e64 v38, v38, v41, s[18:19]
	v_mul_f32_e32 v41, v42, v38
	v_fmamk_f32 v38, v46, 0x3f07dc22, v192
	v_mul_f32_e32 v42, 0xbf38aa3b, v55
	v_fmaak_f32 v38, v46, v38, 0x3f35f0e3
	v_exp_f32_e32 v42, v42
	v_fmaak_f32 v38, v46, v38, 0xbe11a98e
	v_fmaak_f32 v38, v46, v38, 0x3e027906
	v_mul_f32_e32 v38, v46, v38
	v_cndmask_b32_e64 v55, v93, v91, s[4:5]
	v_mul_f32_e32 v38, v42, v38
	v_pk_mul_f32 v[54:55], v[74:75], v[54:55]
	v_pk_mul_f32 v[60:61], v[74:75], v[60:61]
	v_mul_f32_e32 v42, v49, v38
	v_fma_f32 v48, -v49, v38, v49
	v_mov_b32_e32 v50, v47
	v_mov_b32_e32 v38, v71
	v_mov_b32_e32 v46, v60
	v_mov_b32_e32 v47, v54
	v_pk_fma_f32 v[46:47], v[50:51], v[38:39], v[46:47] op_sel_hi:[1,0,1]
	v_mov_b32_e32 v54, v61
	v_pk_add_f32 v[46:47], v[46:47], v[54:55]
	v_mov_b32_e32 v38, v67
	v_pk_add_f32 v[46:47], v[38:39], v[46:47] op_sel_hi:[0,1]
	v_fma_f32 v38, |v47|, s74, 1.0
	v_rcp_f32_e32 v38, v38
	v_cmp_gt_f32_e64 s[18:19], 0, v49
	v_cmp_gt_f32_e64 s[20:21], 0, v47
	v_mov_b64_e32 v[50:51], s[26:27]
	v_cndmask_b32_e64 v42, v48, v42, s[18:19]
	v_mul_f32_e32 v48, v43, v42
	v_fmamk_f32 v42, v38, 0x3f07dc22, v192
	v_fmaak_f32 v49, v38, v42, 0x3f35f0e3
	v_pk_mul_f32 v[42:43], v[46:47], v[46:47]
	v_fmaak_f32 v49, v38, v49, 0xbe11a98e
	v_mul_f32_e32 v43, 0xbf38aa3b, v43
	v_exp_f32_e32 v43, v43
	v_fmaak_f32 v49, v38, v49, 0x3e027906
	v_mul_f32_e32 v38, v38, v49
	v_cmp_gt_f32_e32 vcc, 0, v56
	v_mul_f32_e32 v38, v43, v38
	v_mul_f32_e32 v43, v47, v38
	v_fma_f32 v38, -v47, v38, v47
	v_cndmask_b32_e64 v38, v38, v43, s[20:21]
	v_mul_f32_e32 v43, v39, v38
	v_cvt_pk_bf16_f32 v39, v41, v48
	v_or_b32_e32 v41, s47, v183
	v_mad_i64_i32 v[48:49], s[20:21], v41, s75, v[50:51]
	v_lshl_add_u64 v[48:49], v[48:49], 0, v[112:113]
	v_cvt_pk_bf16_f32 v38, v59, v68
	global_store_dwordx2 v[48:49], v[38:39], off
	v_cvt_pk_bf16_f32 v39, v37, v43
	v_or_b32_e32 v37, s47, v184
	v_mad_i64_i32 v[50:51], s[20:21], v37, s75, v[50:51]
	v_cmp_gt_f32_e64 s[14:15], 0, v44
	v_cmp_gt_f32_e64 s[16:17], 0, v52
	v_cmp_gt_f32_e64 s[18:19], 0, v46
	v_cvt_pk_bf16_f32 v38, v57, v45
	v_lshl_add_u64 v[50:51], v[50:51], 0, v[112:113]
	v_or_b32_e32 v57, s47, v185
	global_store_dwordx2 v[50:51], v[38:39], off
	s_and_saveexec_b64 s[20:21], s[6:7]
	s_cbranch_execz .LBB0_909
	v_fma_f32 v37, |v56|, s74, 1.0
	v_rcp_f32_e32 v37, v37
	v_mul_f32_e32 v38, 0xbf38aa3b, v58
	v_exp_f32_e32 v38, v38
	v_fma_f32 v39, |v44|, s74, 1.0
	v_fmamk_f32 v41, v37, 0x3f07dc22, v192
	v_fmaak_f32 v41, v37, v41, 0x3f35f0e3
	v_fmaak_f32 v41, v37, v41, 0xbe11a98e
	v_fmaak_f32 v41, v37, v41, 0x3e027906
	v_mul_f32_e32 v37, v37, v41
	v_rcp_f32_e32 v39, v39
	v_mul_f32_e32 v37, v38, v37
	v_mul_f32_e32 v38, v56, v37
	v_fma_f32 v37, -v56, v37, v56
	v_cndmask_b32_e32 v37, v37, v38, vcc
	v_mul_f32_e32 v32, v32, v37
	v_fmamk_f32 v37, v39, 0x3f07dc22, v192
	v_fmaak_f32 v37, v39, v37, 0x3f35f0e3
	v_mul_f32_e32 v38, 0xbf38aa3b, v40
	v_exp_f32_e32 v38, v38
	v_fmaak_f32 v37, v39, v37, 0xbe11a98e
	v_fmaak_f32 v37, v39, v37, 0x3e027906
	v_mul_f32_e32 v37, v39, v37
	v_fma_f32 v39, |v52|, s74, 1.0
	v_rcp_f32_e32 v39, v39
	v_mul_f32_e32 v37, v38, v37
	v_mul_f32_e32 v38, v44, v37
	v_fma_f32 v37, -v44, v37, v44
	v_cndmask_b32_e64 v37, v37, v38, s[14:15]
	v_mul_f32_e32 v33, v33, v37
	v_fmamk_f32 v37, v39, 0x3f07dc22, v192
	v_mul_f32_e32 v36, 0xbf38aa3b, v36
	v_fmaak_f32 v37, v39, v37, 0x3f35f0e3
	v_exp_f32_e32 v36, v36
	v_fmaak_f32 v37, v39, v37, 0xbe11a98e
	v_fmaak_f32 v37, v39, v37, 0x3e027906
	v_fma_f32 v38, |v46|, s74, 1.0
	v_mul_f32_e32 v37, v39, v37
	v_rcp_f32_e32 v38, v38
	v_mul_f32_e32 v36, v36, v37
	v_mul_f32_e32 v37, v52, v36
	v_fma_f32 v36, -v52, v36, v52
	v_cndmask_b32_e64 v36, v36, v37, s[16:17]
	v_mul_f32_e32 v34, v34, v36
	v_fmamk_f32 v36, v38, 0x3f07dc22, v192
	v_mul_f32_e32 v37, 0xbf38aa3b, v42
	v_fmaak_f32 v36, v38, v36, 0x3f35f0e3
	v_exp_f32_e32 v37, v37
	v_fmaak_f32 v36, v38, v36, 0xbe11a98e
	v_fmaak_f32 v36, v38, v36, 0x3e027906
	v_mul_f32_e32 v36, v38, v36
	v_mul_f32_e32 v36, v37, v36
	v_mul_f32_e32 v37, v46, v36
	v_fma_f32 v36, -v46, v36, v46
	v_cndmask_b32_e64 v36, v36, v37, s[18:19]
	v_mul_f32_e32 v35, v35, v36
	v_cvt_pk_bf16_f32 v32, v32, v33
	v_cvt_pk_bf16_f32 v33, v34, v35
	v_mov_b64_e32 v[34:35], s[26:27]
	v_mad_i64_i32 v[34:35], s[14:15], v57, s75, v[34:35]
	v_lshl_add_u64 v[34:35], v[168:169], 1, v[34:35]
	global_store_dwordx2 v[34:35], v[32:33], off
; __device__ __forceinline__ unsigned pk2(float lo, float hi) { unsigned r; asm("v_cvt_pk_bf16_f32 %0, %1, %2" : "=v"(r) : "v"(lo), "v"(hi)); return r; }
;     __device__ bool next(int i, pg8::Unit& u) const { if (!base.next(i >> 1, u)) return false; u.seg = i & 1; return true; }
;     __device__ __forceinline__ void operator()(const f32x4 (&acc)[2][2][4][2], const pg8::Unit& u, int wr, int wc, int fr, int fq) const {
;     ...
;             for (int n = 0; n < 2; ++n) {
;                 const f32x4 w0 = *(const f32x4*)(cw + j0 + 4 * n), w1 = *(const f32x4*)(cw + DFF + j0 + 4 * n), w2 = *(const f32x4*)(cw + 2 * DFF + j0 + 4 * n), bs = *(const f32x4*)(cb + j0 + 4 * n);
;                 f32x4 o[4];
; #pragma unroll
;                 for (int e = 0; e < 4; ++e) {
;                     float t[4], sx[4];
; #pragma unroll
;                     for (int m = 0; m < 4; ++m) { const float gv = acc[ai][0][m][n][e]; t[m] = __shfl(gv, psrc); sx[m] = __shfl(gv, nsrc); }
; #pragma unroll
;                     for (int m = 0; m < 4; ++m) { const float gv = acc[ai][0][m][n][e];
;                         const float prev = (fr == 0) ? (m > 0 ? t[m > 0 ? m - 1 : 0] : 0.f) : t[m];
;                         const float next = (fr == 15) ? (m < 3 ? sx[m < 3 ? m + 1 : 3] : 0.f) : sx[m];
;                         const float y = w0[e] * prev + w1[e] * gv + w2[e] * next + bs[e];
;                         o[m][e] = gelu_f(y) * acc[ai][1][m][n][e]; } }
; #pragma unroll
;                 for (int m = 0; m < 4; ++m) { const int rho = 16 * m + fr;
;                     if (rho != 0 && rho != 63) { u32x2 wv; wv.x = pk2(o[m][0], o[m][1]); wv.y = pk2(o[m][2], o[m][3]);
;                         *(u32x2*)(act + (size_t)(kb * 64 + rho) * DFF + j0 + 4 * n) = wv; } }
.LBB0_909:
	s_or_b64 exec, exec, s[20:21]
	s_waitcnt vmcnt(2)
	v_mov_b32_e32 v44, v226
	v_mov_b32_e32 v45, v227
	v_mov_b32_e32 v46, v228
	v_mov_b32_e32 v47, v229
	v_mov_b32_e32 v36, v230
	v_mov_b32_e32 v37, v231
	v_mov_b32_e32 v38, v232
	v_mov_b32_e32 v39, v233
	v_mov_b32_e32 v40, v234
	v_mov_b32_e32 v41, v235
	v_mov_b32_e32 v42, v236
	v_mov_b32_e32 v43, v237
	v_mov_b32_e32 v32, v238
	v_mov_b32_e32 v33, v239
	v_mov_b32_e32 v34, v240
	v_mov_b32_e32 v35, v241
	ds_bpermute_b32 v54, v190, v28
	ds_bpermute_b32 v81, v191, v28
	ds_bpermute_b32 v74, v190, v20
	ds_bpermute_b32 v75, v191, v20
	ds_bpermute_b32 v78, v190, v16
	ds_bpermute_b32 v76, v191, v16
	ds_bpermute_b32 v80, v190, v8
	ds_bpermute_b32 v79, v191, v8
	ds_bpermute_b32 v55, v190, v29
	ds_bpermute_b32 v82, v191, v29
	ds_bpermute_b32 v72, v190, v21
	ds_bpermute_b32 v77, v191, v21
	ds_bpermute_b32 v69, v190, v17
	ds_bpermute_b32 v73, v191, v17
	ds_bpermute_b32 v70, v190, v9
	ds_bpermute_b32 v71, v191, v9
	ds_bpermute_b32 v52, v190, v30
	ds_bpermute_b32 v83, v191, v30
	ds_bpermute_b32 v62, v190, v22
	ds_bpermute_b32 v63, v191, v22
	ds_bpermute_b32 v66, v190, v18
	ds_bpermute_b32 v64, v191, v18
	ds_bpermute_b32 v68, v190, v10
	ds_bpermute_b32 v67, v191, v10
	ds_bpermute_b32 v53, v190, v31
	ds_bpermute_b32 v84, v191, v31
	ds_bpermute_b32 v60, v190, v23
	ds_bpermute_b32 v65, v191, v23
	ds_bpermute_b32 v56, v190, v19
	ds_bpermute_b32 v61, v191, v19
	ds_bpermute_b32 v58, v190, v11
	ds_bpermute_b32 v59, v191, v11
	s_and_saveexec_b64 s[14:15], s[8:9]
	s_cbranch_execz .LBB0_911
	s_waitcnt lgkmcnt(4)
	v_cndmask_b32_e64 v85, v84, v65, s[4:5]
	v_mov_b32_e32 v86, v31
	v_mov_b32_e32 v87, v43
	v_mov_b32_e32 v84, v39
	v_pk_mul_f32 v[84:85], v[86:87], v[84:85]
	v_cndmask_b32_e64 v87, v83, v63, s[4:5]
	v_mov_b32_e32 v31, v42
	v_mov_b32_e32 v86, v38
	v_pk_mul_f32 v[30:31], v[30:31], v[86:87]
	v_mov_b32_e32 v87, v84
	v_mov_b32_e32 v86, v30
	v_pk_fma_f32 v[86:87], v[46:47], v[52:53], v[86:87]
	v_mov_b32_e32 v84, v31
	v_pk_add_f32 v[30:31], v[86:87], v[84:85]
	v_pk_add_f32 v[30:31], v[34:35], v[30:31]
	s_nop 0
	v_fma_f32 v83, |v31|, s74, 1.0
	v_rcp_f32_e32 v83, v83
	v_pk_mul_f32 v[84:85], v[30:31], v[30:31]
	v_cmp_gt_f32_e32 vcc, 0, v31
	v_mul_f32_e32 v85, 0xbf38aa3b, v85
	v_fmamk_f32 v86, v83, 0x3f07dc22, v192
	v_exp_f32_e32 v85, v85
	v_fmaak_f32 v86, v83, v86, 0x3f35f0e3
	v_fmaak_f32 v86, v83, v86, 0xbe11a98e
	v_fmaak_f32 v86, v83, v86, 0x3e027906
	v_mul_f32_e32 v83, v83, v86
	v_mul_f32_e32 v83, v85, v83
	v_mul_f32_e32 v85, v31, v83
	v_fma_f32 v83, -v31, v83, v31
	v_cndmask_b32_e32 v31, v83, v85, vcc
	v_fma_f32 v83, |v30|, s74, 1.0
	v_rcp_f32_e32 v83, v83
	v_mul_f32_e32 v85, v27, v31
	v_mul_f32_e32 v27, 0xbf38aa3b, v84
	v_exp_f32_e32 v27, v27
	v_fmamk_f32 v31, v83, 0x3f07dc22, v192
	v_fmaak_f32 v31, v83, v31, 0x3f35f0e3
	v_fmaak_f32 v31, v83, v31, 0xbe11a98e
	v_fmaak_f32 v31, v83, v31, 0x3e027906
	v_mul_f32_e32 v31, v83, v31
	v_mul_f32_e32 v27, v27, v31
	v_mul_f32_e32 v31, v30, v27
	v_fma_f32 v27, -v30, v27, v30
	v_cmp_gt_f32_e32 vcc, 0, v30
	v_mov_b32_e32 v30, v29
	v_mov_b32_e32 v29, v40
	v_cndmask_b32_e32 v27, v27, v31, vcc
	v_mul_f32_e32 v83, v26, v27
	v_cndmask_b32_e64 v27, v82, v77, s[4:5]
	v_mov_b32_e32 v31, v41
	v_mov_b32_e32 v26, v37
	v_pk_mul_f32 v[26:27], v[30:31], v[26:27]
	v_cndmask_b32_e64 v31, v81, v75, s[4:5]
	v_mov_b32_e32 v30, v36
	v_pk_mul_f32 v[28:29], v[28:29], v[30:31]
	v_mov_b32_e32 v31, v26
	v_mov_b32_e32 v30, v28
	v_pk_fma_f32 v[30:31], v[44:45], v[54:55], v[30:31]
	v_mov_b32_e32 v26, v29
	v_pk_add_f32 v[26:27], v[30:31], v[26:27]
	s_nop 0
	v_pk_add_f32 v[26:27], v[32:33], v[26:27]
	s_nop 0
	v_fma_f32 v28, |v27|, s74, 1.0
	v_rcp_f32_e32 v30, v28
	v_pk_mul_f32 v[28:29], v[26:27], v[26:27]
	v_cmp_gt_f32_e32 vcc, 0, v27
	v_mul_f32_e32 v29, 0xbf38aa3b, v29
	v_fmamk_f32 v31, v30, 0x3f07dc22, v192
	v_exp_f32_e32 v29, v29
	v_fmaak_f32 v31, v30, v31, 0x3f35f0e3
	v_fmaak_f32 v31, v30, v31, 0xbe11a98e
	v_fmaak_f32 v31, v30, v31, 0x3e027906
	v_mul_f32_e32 v30, v30, v31
	v_mul_f32_e32 v29, v29, v30
	v_mul_f32_e32 v30, v27, v29
	v_fma_f32 v29, -v27, v29, v27
	v_cndmask_b32_e32 v27, v29, v30, vcc
	v_fma_f32 v29, |v26|, s74, 1.0
	v_rcp_f32_e32 v29, v29
	v_mul_f32_e32 v25, v25, v27
	v_mul_f32_e32 v27, 0xbf38aa3b, v28
	v_exp_f32_e32 v27, v27
	v_fmamk_f32 v28, v29, 0x3f07dc22, v192
	v_fmaak_f32 v28, v29, v28, 0x3f35f0e3
	v_fmaak_f32 v28, v29, v28, 0xbe11a98e
	v_fmaak_f32 v28, v29, v28, 0x3e027906
	v_mul_f32_e32 v28, v29, v28
	v_mul_f32_e32 v27, v27, v28
	v_mul_f32_e32 v28, v26, v27
	v_fma_f32 v27, -v26, v27, v26
	v_cmp_gt_f32_e32 vcc, 0, v26
	s_nop 1
	v_cndmask_b32_e32 v26, v27, v28, vcc
	v_mul_f32_e32 v24, v24, v26
	v_mov_b64_e32 v[26:27], s[26:27]
	v_mad_i64_i32 v[26:27], s[16:17], v88, s75, v[26:27]
	v_lshl_add_u64 v[26:27], v[168:169], 1, v[26:27]
	v_cvt_pk_bf16_f32 v24, v24, v25
	v_cvt_pk_bf16_f32 v25, v83, v85
	global_store_dwordx2 v[26:27], v[24:25], off offset:8
; __device__ __forceinline__ unsigned pk2(float lo, float hi) { unsigned r; asm("v_cvt_pk_bf16_f32 %0, %1, %2" : "=v"(r) : "v"(lo), "v"(hi)); return r; }
;     __device__ bool next(int i, pg8::Unit& u) const { if (!base.next(i >> 1, u)) return false; u.seg = i & 1; return true; }
;     __device__ __forceinline__ void operator()(const f32x4 (&acc)[2][2][4][2], const pg8::Unit& u, int wr, int wc, int fr, int fq) const {
;     ...
;             for (int n = 0; n < 2; ++n) {
;                 const f32x4 w0 = *(const f32x4*)(cw + j0 + 4 * n), w1 = *(const f32x4*)(cw + DFF + j0 + 4 * n), w2 = *(const f32x4*)(cw + 2 * DFF + j0 + 4 * n), bs = *(const f32x4*)(cb + j0 + 4 * n);
;                 f32x4 o[4];
; #pragma unroll
;                 for (int e = 0; e < 4; ++e) {
;                     float t[4], sx[4];
; #pragma unroll
;                     for (int m = 0; m < 4; ++m) { const float gv = acc[ai][0][m][n][e]; t[m] = __shfl(gv, psrc); sx[m] = __shfl(gv, nsrc); }
; #pragma unroll
;                     for (int m = 0; m < 4; ++m) { const float gv = acc[ai][0][m][n][e];
;                         const float prev = (fr == 0) ? (m > 0 ? t[m > 0 ? m - 1 : 0] : 0.f) : t[m];
;                         const float next = (fr == 15) ? (m < 3 ? sx[m < 3 ? m + 1 : 3] : 0.f) : sx[m];
;                         const float y = w0[e] * prev + w1[e] * gv + w2[e] * next + bs[e];
;                         o[m][e] = gelu_f(y) * acc[ai][1][m][n][e]; } }
; #pragma unroll
;                 for (int m = 0; m < 4; ++m) { const int rho = 16 * m + fr;
;                     if (rho != 0 && rho != 63) { u32x2 wv; wv.x = pk2(o[m][0], o[m][1]); wv.y = pk2(o[m][2], o[m][3]);
;                         *(u32x2*)(act + (size_t)(kb * 64 + rho) * DFF + j0 + 4 * n) = wv; } }
.LBB0_911:
	s_or_b64 exec, exec, s[14:15]
	v_mov_b32_e32 v28, v44
	v_mov_b32_e32 v29, v40
	s_waitcnt lgkmcnt(14)
	v_cndmask_b32_e64 v24, v80, v78, s[10:11]
	v_cndmask_b32_e64 v25, v79, 0, s[4:5]
	v_cndmask_b32_e64 v26, v78, v74, s[10:11]
	v_cndmask_b32_e64 v27, v76, v79, s[4:5]
	v_pk_mul_f32 v[24:25], v[28:29], v[24:25]
	v_pk_mul_f32 v[26:27], v[28:29], v[26:27]
	v_mov_b32_e32 v30, v8
	v_mov_b32_e32 v31, v16
	v_mov_b32_e32 v78, v24
	v_mov_b32_e32 v79, v26
	v_pk_fma_f32 v[30:31], v[30:31], v[36:37], v[78:79] op_sel_hi:[1,0,1]
	v_mov_b32_e32 v26, v25
	v_pk_add_f32 v[24:25], v[30:31], v[26:27]
	v_cndmask_b32_e64 v30, v74, v54, s[10:11]
	v_pk_add_f32 v[24:25], v[32:33], v[24:25] op_sel_hi:[0,1]
	v_fma_f32 v8, |v25|, s74, 1.0
	v_rcp_f32_e32 v8, v8
	v_cndmask_b32_e64 v31, v75, v76, s[4:5]
	v_pk_mul_f32 v[26:27], v[24:25], v[24:25]
	v_pk_mul_f32 v[28:29], v[28:29], v[30:31]
	v_cndmask_b32_e64 v30, v72, v55, s[10:11]
	v_cndmask_b32_e64 v31, v77, v73, s[4:5]
	v_mov_b32_e32 v40, v45
	v_fmamk_f32 v16, v8, 0x3f07dc22, v192
	v_mul_f32_e32 v27, 0xbf38aa3b, v27
	v_pk_mul_f32 v[30:31], v[40:41], v[30:31]
	v_fmaak_f32 v16, v8, v16, 0x3f35f0e3
	v_exp_f32_e32 v27, v27
	v_mov_b32_e32 v44, v28
	v_mov_b32_e32 v45, v30
	v_fmaak_f32 v16, v8, v16, 0xbe11a98e
	v_pk_fma_f32 v[20:21], v[20:21], v[36:37], v[44:45]
	v_mov_b32_e32 v30, v29
	v_fmaak_f32 v16, v8, v16, 0x3e027906
	v_pk_add_f32 v[20:21], v[20:21], v[30:31]
	v_mul_f32_e32 v8, v8, v16
	v_pk_add_f32 v[20:21], v[32:33], v[20:21]
	v_mul_f32_e32 v8, v27, v8
	v_fma_f32 v27, |v20|, s74, 1.0
	v_rcp_f32_e32 v27, v27
	v_mul_f32_e32 v16, v25, v8
	v_fma_f32 v8, -v25, v8, v25
	v_cmp_gt_f32_e64 s[14:15], 0, v25
	v_pk_mul_f32 v[28:29], v[20:21], v[20:21]
	v_cndmask_b32_e64 v30, v70, v69, s[10:11]
	v_cndmask_b32_e64 v8, v8, v16, s[14:15]
	v_mul_f32_e32 v25, v4, v8
	v_fmamk_f32 v4, v27, 0x3f07dc22, v192
	v_mul_f32_e32 v8, 0xbf38aa3b, v28
	v_fmaak_f32 v4, v27, v4, 0x3f35f0e3
	v_exp_f32_e32 v8, v8
	v_fmaak_f32 v4, v27, v4, 0xbe11a98e
	v_fmaak_f32 v4, v27, v4, 0x3e027906
	v_fma_f32 v16, |v21|, s74, 1.0
	v_mul_f32_e32 v4, v27, v4
	v_rcp_f32_e32 v16, v16
	v_mul_f32_e32 v4, v8, v4
	v_mul_f32_e32 v8, v20, v4
	v_fma_f32 v4, -v20, v4, v20
	v_cmp_gt_f32_e64 s[14:15], 0, v20
	v_cndmask_b32_e64 v28, v69, v72, s[10:11]
	v_cndmask_b32_e64 v31, v71, 0, s[4:5]
	v_cndmask_b32_e64 v4, v4, v8, s[14:15]
	v_mul_f32_e32 v27, v12, v4
	v_fmamk_f32 v4, v16, 0x3f07dc22, v192
	v_mul_f32_e32 v8, 0xbf38aa3b, v29
	v_fmaak_f32 v4, v16, v4, 0x3f35f0e3
	v_exp_f32_e32 v8, v8
	v_fmaak_f32 v4, v16, v4, 0xbe11a98e
	v_fmaak_f32 v4, v16, v4, 0x3e027906
	v_cndmask_b32_e64 v29, v73, v71, s[4:5]
	v_mul_f32_e32 v4, v16, v4
	v_pk_mul_f32 v[28:29], v[40:41], v[28:29]
	v_pk_mul_f32 v[30:31], v[40:41], v[30:31]
	v_mul_f32_e32 v4, v8, v4
	v_mov_b32_e32 v16, v9
	v_mov_b32_e32 v8, v30
	v_mov_b32_e32 v9, v28
	v_pk_fma_f32 v[8:9], v[16:17], v[36:37], v[8:9] op_sel:[0,1,0]
	v_mov_b32_e32 v28, v31
	v_pk_add_f32 v[8:9], v[8:9], v[28:29]
	v_mul_f32_e32 v12, v21, v4
	v_pk_add_f32 v[8:9], v[32:33], v[8:9] op_sel:[1,0]
	v_fma_f32 v4, -v21, v4, v21
	v_fma_f32 v16, |v9|, s74, 1.0
	v_rcp_f32_e32 v16, v16
	v_cmp_gt_f32_e64 s[14:15], 0, v21
	v_mov_b32_e32 v20, v46
	v_mov_b32_e32 v21, v42
	v_cndmask_b32_e64 v4, v4, v12, s[14:15]
	v_mul_f32_e32 v36, v13, v4
	v_fmamk_f32 v4, v16, 0x3f07dc22, v192
	v_fmaak_f32 v4, v16, v4, 0x3f35f0e3
	v_fmaak_f32 v4, v16, v4, 0xbe11a98e
	v_pk_mul_f32 v[12:13], v[8:9], v[8:9]
	v_fmaak_f32 v4, v16, v4, 0x3e027906
	v_mul_f32_e32 v13, 0xbf38aa3b, v13
	v_mul_f32_e32 v4, v16, v4
	s_waitcnt lgkmcnt(9)
	v_cndmask_b32_e64 v16, v68, v66, s[10:11]
	s_waitcnt lgkmcnt(8)
	v_cndmask_b32_e64 v17, v67, 0, s[4:5]
	v_cndmask_b32_e64 v28, v66, v62, s[10:11]
	v_cndmask_b32_e64 v29, v64, v67, s[4:5]
	v_exp_f32_e32 v13, v13
	v_pk_mul_f32 v[16:17], v[20:21], v[16:17]
	v_pk_mul_f32 v[28:29], v[20:21], v[28:29]
	v_mov_b32_e32 v30, v10
	v_mov_b32_e32 v31, v18
	v_mov_b32_e32 v32, v16
	v_mov_b32_e32 v33, v28
	v_pk_fma_f32 v[30:31], v[30:31], v[38:39], v[32:33] op_sel_hi:[1,0,1]
	v_mov_b32_e32 v28, v17
	v_pk_add_f32 v[16:17], v[30:31], v[28:29]
	v_mul_f32_e32 v4, v13, v4
	v_pk_add_f32 v[16:17], v[34:35], v[16:17] op_sel_hi:[0,1]
	v_mul_f32_e32 v13, v9, v4
	v_fma_f32 v4, -v9, v4, v9
	v_cmp_gt_f32_e64 s[16:17], 0, v9
	v_fma_f32 v9, |v17|, s74, 1.0
	v_rcp_f32_e32 v9, v9
	v_cndmask_b32_e64 v28, v62, v52, s[10:11]
	v_cndmask_b32_e64 v29, v63, v64, s[4:5]
	v_pk_mul_f32 v[20:21], v[20:21], v[28:29]
	s_waitcnt lgkmcnt(5)
	v_cndmask_b32_e64 v28, v60, v53, s[10:11]
	s_waitcnt lgkmcnt(2)
; __device__ __forceinline__ unsigned pk2(float lo, float hi) { unsigned r; asm("v_cvt_pk_bf16_f32 %0, %1, %2" : "=v"(r) : "v"(lo), "v"(hi)); return r; }
;     __device__ bool next(int i, pg8::Unit& u) const { if (!base.next(i >> 1, u)) return false; u.seg = i & 1; return true; }
;     __device__ __forceinline__ void operator()(const f32x4 (&acc)[2][2][4][2], const pg8::Unit& u, int wr, int wc, int fr, int fq) const {
;     ...
;                     for (int m = 0; m < 4; ++m) { const float gv = acc[ai][0][m][n][e];
;                         const float prev = (fr == 0) ? (m > 0 ? t[m > 0 ? m - 1 : 0] : 0.f) : t[m];
;                         const float next = (fr == 15) ? (m < 3 ? sx[m < 3 ? m + 1 : 3] : 0.f) : sx[m];
;                         const float y = w0[e] * prev + w1[e] * gv + w2[e] * next + bs[e];
;                         o[m][e] = gelu_f(y) * acc[ai][1][m][n][e]; } }
; #pragma unroll
;                 for (int m = 0; m < 4; ++m) { const int rho = 16 * m + fr;
;                     if (rho != 0 && rho != 63) { u32x2 wv; wv.x = pk2(o[m][0], o[m][1]); wv.y = pk2(o[m][2], o[m][3]);
;                         *(u32x2*)(act + (size_t)(kb * 64 + rho) * DFF + j0 + 4 * n) = wv; } }
	v_cndmask_b32_e64 v29, v65, v61, s[4:5]
	v_mov_b32_e32 v42, v47
	v_cndmask_b32_e64 v4, v4, v13, s[16:17]
	v_pk_mul_f32 v[28:29], v[42:43], v[28:29]
	v_mul_f32_e32 v13, v5, v4
	v_pk_mul_f32 v[4:5], v[16:17], v[16:17]
	v_fmamk_f32 v10, v9, 0x3f07dc22, v192
	v_mov_b32_e32 v30, v20
	v_mov_b32_e32 v31, v28
	v_fmaak_f32 v10, v9, v10, 0x3f35f0e3
	v_mul_f32_e32 v5, 0xbf38aa3b, v5
	v_pk_fma_f32 v[22:23], v[22:23], v[38:39], v[30:31]
	v_mov_b32_e32 v28, v21
	v_exp_f32_e32 v5, v5
	v_fmaak_f32 v10, v9, v10, 0xbe11a98e
	v_pk_add_f32 v[20:21], v[22:23], v[28:29]
	v_fmaak_f32 v10, v9, v10, 0x3e027906
	v_pk_add_f32 v[20:21], v[34:35], v[20:21]
	v_mul_f32_e32 v9, v9, v10
	v_fma_f32 v10, |v20|, s74, 1.0
	v_rcp_f32_e32 v10, v10
	v_mul_f32_e32 v5, v5, v9
	v_mul_f32_e32 v9, v17, v5
	v_fma_f32 v5, -v17, v5, v17
	v_cmp_gt_f32_e64 s[18:19], 0, v17
	v_pk_mul_f32 v[22:23], v[20:21], v[20:21]
	s_waitcnt lgkmcnt(1)
	v_cndmask_b32_e64 v28, v58, v56, s[10:11]
	v_cndmask_b32_e64 v5, v5, v9, s[18:19]
	v_mul_f32_e32 v5, v6, v5
	v_fmamk_f32 v6, v10, 0x3f07dc22, v192
	v_fmaak_f32 v6, v10, v6, 0x3f35f0e3
	v_mul_f32_e32 v9, 0xbf38aa3b, v22
	v_exp_f32_e32 v9, v9
	v_fmaak_f32 v6, v10, v6, 0xbe11a98e
	v_fmaak_f32 v6, v10, v6, 0x3e027906
	v_mul_f32_e32 v6, v10, v6
	v_fma_f32 v10, |v21|, s74, 1.0
	v_rcp_f32_e32 v10, v10
	v_mul_f32_e32 v6, v9, v6
	v_mul_f32_e32 v9, v20, v6
	v_fma_f32 v6, -v20, v6, v20
	v_cmp_gt_f32_e64 s[18:19], 0, v20
	v_cndmask_b32_e64 v22, v56, v60, s[10:11]
	s_waitcnt lgkmcnt(0)
	v_cndmask_b32_e64 v29, v59, 0, s[4:5]
	v_cndmask_b32_e64 v6, v6, v9, s[18:19]
	v_mul_f32_e32 v9, v14, v6
	v_fmamk_f32 v6, v10, 0x3f07dc22, v192
	v_mul_f32_e32 v14, 0xbf38aa3b, v23
	v_fmaak_f32 v6, v10, v6, 0x3f35f0e3
	v_exp_f32_e32 v14, v14
	v_fmaak_f32 v6, v10, v6, 0xbe11a98e
	v_fmaak_f32 v6, v10, v6, 0x3e027906
	v_mul_f32_e32 v6, v10, v6
	v_cndmask_b32_e64 v23, v61, v59, s[4:5]
	v_mul_f32_e32 v6, v14, v6
	v_pk_mul_f32 v[22:23], v[42:43], v[22:23]
	v_pk_mul_f32 v[28:29], v[42:43], v[28:29]
	v_mul_f32_e32 v14, v21, v6
	v_fma_f32 v17, -v21, v6, v21
	v_mov_b32_e32 v18, v11
	v_mov_b32_e32 v6, v39
	v_mov_b32_e32 v10, v28
	v_mov_b32_e32 v11, v22
	v_pk_fma_f32 v[10:11], v[18:19], v[6:7], v[10:11] op_sel_hi:[1,0,1]
	v_mov_b32_e32 v22, v29
	v_pk_add_f32 v[10:11], v[10:11], v[22:23]
	v_mov_b32_e32 v6, v35
	v_pk_add_f32 v[10:11], v[6:7], v[10:11] op_sel_hi:[0,1]
	v_fma_f32 v6, |v11|, s74, 1.0
	v_rcp_f32_e32 v6, v6
	v_cmp_gt_f32_e64 s[18:19], 0, v21
	v_cmp_gt_f32_e64 s[20:21], 0, v11
	v_cmp_gt_f32_e32 vcc, 0, v24
	v_cndmask_b32_e64 v14, v17, v14, s[18:19]
	v_mul_f32_e32 v17, v15, v14
	v_fmamk_f32 v14, v6, 0x3f07dc22, v192
	v_fmaak_f32 v18, v6, v14, 0x3f35f0e3
	v_pk_mul_f32 v[14:15], v[10:11], v[10:11]
	v_fmaak_f32 v18, v6, v18, 0xbe11a98e
	v_mul_f32_e32 v15, 0xbf38aa3b, v15
	v_exp_f32_e32 v15, v15
	v_fmaak_f32 v18, v6, v18, 0x3e027906
	v_mul_f32_e32 v6, v6, v18
	v_cmp_gt_f32_e64 s[14:15], 0, v8
	v_mul_f32_e32 v6, v15, v6
	v_mul_f32_e32 v15, v11, v6
	v_fma_f32 v6, -v11, v6, v11
	v_cndmask_b32_e64 v6, v6, v15, s[20:21]
	v_cmp_gt_f32_e64 s[16:17], 0, v16
	v_cmp_gt_f32_e64 s[18:19], 0, v10
	v_mul_f32_e32 v11, v7, v6
	v_cvt_pk_bf16_f32 v6, v27, v36
	v_cvt_pk_bf16_f32 v7, v9, v17
	global_store_dwordx2 v[48:49], v[6:7], off offset:8
	v_cvt_pk_bf16_f32 v6, v25, v13
	v_cvt_pk_bf16_f32 v7, v5, v11
	global_store_dwordx2 v[50:51], v[6:7], off offset:8
	s_and_saveexec_b64 s[20:21], s[6:7]
	s_cbranch_execz .LBB0_913
	v_fma_f32 v5, |v24|, s74, 1.0
	v_rcp_f32_e32 v5, v5
	v_mul_f32_e32 v6, 0xbf38aa3b, v26
	v_exp_f32_e32 v6, v6
	v_fma_f32 v7, |v8|, s74, 1.0
	v_fmamk_f32 v9, v5, 0x3f07dc22, v192
	v_fmaak_f32 v9, v5, v9, 0x3f35f0e3
	v_fmaak_f32 v9, v5, v9, 0xbe11a98e
	v_fmaak_f32 v9, v5, v9, 0x3e027906
	v_mul_f32_e32 v5, v5, v9
	v_rcp_f32_e32 v7, v7
	v_mul_f32_e32 v5, v6, v5
	v_mul_f32_e32 v6, v24, v5
	v_fma_f32 v5, -v24, v5, v24
	v_cndmask_b32_e32 v5, v5, v6, vcc
	v_mul_f32_e32 v0, v0, v5
	v_fmamk_f32 v5, v7, 0x3f07dc22, v192
	v_fmaak_f32 v5, v7, v5, 0x3f35f0e3
	v_mul_f32_e32 v6, 0xbf38aa3b, v12
	v_exp_f32_e32 v6, v6
	v_fmaak_f32 v5, v7, v5, 0xbe11a98e
	v_fmaak_f32 v5, v7, v5, 0x3e027906
	v_mul_f32_e32 v5, v7, v5
	v_fma_f32 v7, |v16|, s74, 1.0
	v_rcp_f32_e32 v7, v7
	v_mul_f32_e32 v5, v6, v5
	v_mul_f32_e32 v6, v8, v5
	v_fma_f32 v5, -v8, v5, v8
	v_cndmask_b32_e64 v5, v5, v6, s[14:15]
	v_mul_f32_e32 v1, v1, v5
	v_fmamk_f32 v5, v7, 0x3f07dc22, v192
	v_mul_f32_e32 v4, 0xbf38aa3b, v4
	v_fmaak_f32 v5, v7, v5, 0x3f35f0e3
	v_exp_f32_e32 v4, v4
	v_fmaak_f32 v5, v7, v5, 0xbe11a98e
	v_fmaak_f32 v5, v7, v5, 0x3e027906
	v_fma_f32 v6, |v10|, s74, 1.0
	v_mul_f32_e32 v5, v7, v5
	v_rcp_f32_e32 v6, v6
	v_mul_f32_e32 v4, v4, v5
	v_mul_f32_e32 v5, v16, v4
	v_fma_f32 v4, -v16, v4, v16
	v_cndmask_b32_e64 v4, v4, v5, s[16:17]
	v_mul_f32_e32 v2, v2, v4
	v_fmamk_f32 v4, v6, 0x3f07dc22, v192
	v_mul_f32_e32 v5, 0xbf38aa3b, v14
	v_fmaak_f32 v4, v6, v4, 0x3f35f0e3
	v_exp_f32_e32 v5, v5
	v_fmaak_f32 v4, v6, v4, 0xbe11a98e
	v_fmaak_f32 v4, v6, v4, 0x3e027906
	v_mul_f32_e32 v4, v6, v4
	v_mul_f32_e32 v4, v5, v4
	v_mul_f32_e32 v5, v10, v4
	v_fma_f32 v4, -v10, v4, v10
	v_cndmask_b32_e64 v4, v4, v5, s[18:19]
	v_mul_f32_e32 v3, v3, v4
	v_cvt_pk_bf16_f32 v0, v0, v1
	v_cvt_pk_bf16_f32 v1, v2, v3
	v_mov_b64_e32 v[2:3], s[26:27]
	v_mad_i64_i32 v[2:3], s[14:15], v57, s75, v[2:3]
	v_lshl_add_u64 v[2:3], v[168:169], 1, v[2:3]
	global_store_dwordx2 v[2:3], v[0:1], off offset:8
